# conv epilogue: 16 ds_bpermute reduction hops per unit replaced by v_permlane16/32_swap (LDS-free cross-lane reduction), on top of v9
# baseline (speedup 1.0000x reference)
;     __device__ __forceinline__ void operator()(f32x4 (&acc)[2][2][4][2], const Unit& u, int wr, int wc, int fr, int fq, PG8_LAS unsigned char* lds) const {
;     ...
;                 for (int m = 0; m < 4; ++m) {
;                     const f32x4 uc = acc[ai][0][m][1], cb = acc[ai][0][m][0], gt = acc[ai][1][m][1];
;                     f32x4 v1, v2;
; #pragma unroll
;                     for (int i = 0; i < 4; ++i) {
;                         const float s1 = (fr == 15) ? prev[i] : uc[i], s2 = (fr >= 14) ? prev[i] : uc[i];
;                         v1[i] = __int_as_float(__builtin_amdgcn_mov_dpp(__float_as_int(s1), 0x121, 0xf, 0xf, true));
;                         v2[i] = __int_as_float(__builtin_amdgcn_mov_dpp(__float_as_int(s2), 0x122, 0xf, 0xf, true));
;                     }
;                     const f32x4 raw = cb * (w0 * v2 + w1 * v1 + w2 * uc);
;                     float ss = (raw[0] * raw[0] + raw[1] * raw[1]) + (raw[2] * raw[2] + raw[3] * raw[3]);
;                     ss += __shfl_xor(ss, 16); ss += __shfl_xor(ss, 32);
;                     const int rl = ai * HALF + wr * 64 + m * 16 + fr;
;                     const bool def = deferred_tile && (rl < 2);
;                     if (fq == 0) SSCT[((size_t)u.pm * 64 + j * 4 + wc) * 256 + rl] = def ? 0.f : ss;
.LBB0_144:
	v_pk_mul_f32 v[126:127], v[130:131], v[126:127]
	v_pk_mul_f32 v[128:129], v[132:133], v[128:129]
	s_waitcnt lgkmcnt(0)
	v_cndmask_b32_e64 v131, v126, v138, s[14:15]
	v_cndmask_b32_e64 v133, v127, v139, s[14:15]
	v_cndmask_b32_e64 v130, v126, v138, s[4:5]
	v_mov_b32_dpp v132, v131 row_ror:2 row_mask:0xf bank_mask:0xf bound_ctrl:1
	v_cndmask_b32_e64 v131, v127, v139, s[4:5]
	v_cndmask_b32_e64 v139, v128, v140, s[14:15]
	v_cndmask_b32_e64 v138, v128, v140, s[4:5]
	v_mov_b32_dpp v133, v133 row_ror:2 row_mask:0xf bank_mask:0xf bound_ctrl:1
	v_mov_b32_dpp v140, v139 row_ror:2 row_mask:0xf bank_mask:0xf bound_ctrl:1
	v_cndmask_b32_e64 v139, v129, v141, s[4:5]
	v_cndmask_b32_e64 v141, v129, v141, s[14:15]
	v_mov_b32_dpp v130, v130 row_ror:1 row_mask:0xf bank_mask:0xf bound_ctrl:1
	v_mov_b32_dpp v131, v131 row_ror:1 row_mask:0xf bank_mask:0xf bound_ctrl:1
	v_mov_b32_dpp v141, v141 row_ror:2 row_mask:0xf bank_mask:0xf bound_ctrl:1
	v_mov_b32_dpp v138, v138 row_ror:1 row_mask:0xf bank_mask:0xf bound_ctrl:1
	v_mov_b32_dpp v139, v139 row_ror:1 row_mask:0xf bank_mask:0xf bound_ctrl:1
	s_waitcnt vmcnt(0)
	v_pk_mul_f32 v[140:141], v[84:85], v[140:141]
	v_pk_mul_f32 v[132:133], v[82:83], v[132:133]
	v_pk_fma_f32 v[138:139], v[78:79], v[138:139], v[140:141]
	v_pk_fma_f32 v[130:131], v[76:77], v[130:131], v[132:133]
	v_and_b32_e32 v189, 64, v187
	v_pk_fma_f32 v[132:133], v[128:129], v[74:75], v[138:139]
	v_pk_fma_f32 v[138:139], v[126:127], v[72:73], v[130:131]
	v_xor_b32_e32 v188, 16, v187
	v_add_u32_e32 v189, 64, v189
	v_pk_mul_f32 v[130:131], v[124:125], v[132:133]
	v_pk_mul_f32 v[132:133], v[122:123], v[138:139]
	v_cmp_lt_i32_e32 vcc, v188, v189
	v_mul_f32_e32 v138, v133, v133
	v_mul_f32_e32 v139, v131, v131
	v_cndmask_b32_e32 v188, v187, v188, vcc
	v_fmac_f32_e32 v138, v132, v132
	v_fmac_f32_e32 v139, v130, v130
	v_lshlrev_b32_e32 v188, 2, v188
	v_add_f32_e32 v138, v138, v139
	v_mov_b32_e32 v140, v138
	s_nop 1
	v_permlane16_swap_b32_e32 v140, v138
	v_xor_b32_e32 v139, 32, v187
	v_cmp_lt_i32_e32 vcc, v139, v189
	s_and_b32 s0, s74, 7
	s_cmp_lg_u32 s0, 0
	v_cndmask_b32_e32 v139, v187, v139, vcc
	v_lshlrev_b32_e32 v139, 2, v139
	s_waitcnt lgkmcnt(0)
	v_add_f32_e32 v140, v138, v140
	v_mov_b32_e32 v141, v140
	s_nop 1
	v_permlane32_swap_b32_e32 v141, v140
	s_cselect_b64 s[0:1], -1, 0
	s_lshl_b32 s2, s2, 2
	s_or_b32 s68, s2, s26
	s_and_b64 s[0:1], s[0:1], s[8:9]
	v_lshlrev_b32_e32 v138, 2, v148
	s_and_saveexec_b64 s[2:3], s[6:7]
	s_cbranch_execz .LBB0_146
	s_ashr_i32 s75, s74, 31
	s_lshl_b64 s[16:17], s[74:75], 16
	s_lshl_b64 s[36:37], s[68:69], 10
	v_readlane_b32 s38, v253, 40
	v_readlane_b32 s39, v253, 41
	s_add_u32 s16, s38, s16
	s_addc_u32 s17, s39, s17
	s_waitcnt lgkmcnt(0)
	v_add_f32_e32 v140, v140, v141
	s_add_u32 s16, s16, s36
	v_cndmask_b32_e64 v140, v140, 0, s[0:1]
	s_addc_u32 s17, s17, s37
	global_store_dword v138, v140, s[16:17]

; __device__ __forceinline__ unsigned cvt_pk_bf16(float lo, float hi) { unsigned r; asm volatile("v_cvt_pk_bf16_f32 %0, %1, %2" : "=v"(r) : "v"(lo), "v"(hi)); return r; }
; __device__ __forceinline__ float silu_f(float g) { return g * __builtin_amdgcn_rcpf(1.0f + __builtin_amdgcn_exp2f(-1.4426950408889634f * g)); }
;     __device__ __forceinline__ void operator()(f32x4 (&acc)[2][2][4][2], const Unit& u, int wr, int wc, int fr, int fq, PG8_LAS unsigned char* lds) const {
;     ...
;                 for (int m = 0; m < 4; ++m) {
;                     const f32x4 uc = acc[ai][0][m][1], cb = acc[ai][0][m][0], gt = acc[ai][1][m][1];
;                     f32x4 v1, v2;
; #pragma unroll
;                     for (int i = 0; i < 4; ++i) {
;                         const float s1 = (fr == 15) ? prev[i] : uc[i], s2 = (fr >= 14) ? prev[i] : uc[i];
;                         v1[i] = __int_as_float(__builtin_amdgcn_mov_dpp(__float_as_int(s1), 0x121, 0xf, 0xf, true));
;                         v2[i] = __int_as_float(__builtin_amdgcn_mov_dpp(__float_as_int(s2), 0x122, 0xf, 0xf, true));
;                     }
;                     const f32x4 raw = cb * (w0 * v2 + w1 * v1 + w2 * uc);
;                     float ss = (raw[0] * raw[0] + raw[1] * raw[1]) + (raw[2] * raw[2] + raw[3] * raw[3]);
;                     ss += __shfl_xor(ss, 16); ss += __shfl_xor(ss, 32);
;                     const int rl = ai * HALF + wr * 64 + m * 16 + fr;
;                     const bool def = deferred_tile && (rl < 2);
;                     if (fq == 0) SSCT[((size_t)u.pm * 64 + j * 4 + wc) * 256 + rl] = def ? 0.f : ss;
;                     u32x2 z;
;                     z.x = cvt_pk_bf16(raw[0] * gn[0] * silu_f(gt[0]), raw[1] * gn[1] * silu_f(gt[1]));
;                     z.y = cvt_pk_bf16(raw[2] * gn[2] * silu_f(gt[2]), raw[3] * gn[3] * silu_f(gt[3]));
;                     *(u32x2*)(MIX + (size_t)(u.pm * BM + rl) * 2048 + col) = z;
.LBB0_148:
	s_or_b64 exec, exec, s[2:3]
	v_pk_mul_f32 v[112:113], v[120:121], v[112:113]
	v_pk_mul_f32 v[110:111], v[118:119], v[110:111]
	v_cndmask_b32_e64 v119, v112, v128, s[14:15]
	v_cndmask_b32_e64 v115, v110, v126, s[14:15]
	v_cndmask_b32_e64 v117, v111, v127, s[14:15]
	v_cndmask_b32_e64 v121, v113, v129, s[14:15]
	v_cndmask_b32_e64 v114, v110, v126, s[4:5]
	v_mov_b32_dpp v116, v115 row_ror:2 row_mask:0xf bank_mask:0xf bound_ctrl:1
	v_cndmask_b32_e64 v115, v111, v127, s[4:5]
	v_mov_b32_dpp v117, v117 row_ror:2 row_mask:0xf bank_mask:0xf bound_ctrl:1
	v_cndmask_b32_e64 v118, v112, v128, s[4:5]
	v_mov_b32_dpp v120, v119 row_ror:2 row_mask:0xf bank_mask:0xf bound_ctrl:1
	v_cndmask_b32_e64 v119, v113, v129, s[4:5]
	v_mov_b32_dpp v121, v121 row_ror:2 row_mask:0xf bank_mask:0xf bound_ctrl:1
	v_mov_b32_dpp v114, v114 row_ror:1 row_mask:0xf bank_mask:0xf bound_ctrl:1
	v_mov_b32_dpp v115, v115 row_ror:1 row_mask:0xf bank_mask:0xf bound_ctrl:1
	v_mov_b32_dpp v118, v118 row_ror:1 row_mask:0xf bank_mask:0xf bound_ctrl:1
	v_mov_b32_dpp v119, v119 row_ror:1 row_mask:0xf bank_mask:0xf bound_ctrl:1
	v_pk_mul_f32 v[120:121], v[84:85], v[120:121]
	v_pk_mul_f32 v[116:117], v[82:83], v[116:117]
	v_pk_fma_f32 v[118:119], v[78:79], v[118:119], v[120:121]
	v_pk_fma_f32 v[114:115], v[76:77], v[114:115], v[116:117]
	v_pk_fma_f32 v[116:117], v[112:113], v[74:75], v[118:119]
	v_pk_fma_f32 v[114:115], v[110:111], v[72:73], v[114:115]
	v_pk_mul_f32 v[108:109], v[108:109], v[116:117]
	v_pk_mul_f32 v[106:107], v[106:107], v[114:115]
	v_mul_f32_e32 v115, v109, v109
	v_mul_f32_e32 v114, v107, v107
	v_fmac_f32_e32 v114, v106, v106
	v_fmac_f32_e32 v115, v108, v108
	v_add_f32_e32 v114, v114, v115
	v_mov_b32_e32 v115, v114
	s_nop 1
	v_permlane16_swap_b32_e32 v115, v114
	s_waitcnt lgkmcnt(0)
	v_add_f32_e32 v114, v114, v115
	v_mov_b32_e32 v115, v114
	s_nop 1
	v_permlane32_swap_b32_e32 v115, v114
	s_and_saveexec_b64 s[0:1], s[6:7]
	s_cbranch_execz .LBB0_150
	s_ashr_i32 s75, s74, 31
	s_lshl_b64 s[2:3], s[74:75], 16
	s_lshl_b64 s[36:37], s[68:69], 10
	v_readlane_b32 s38, v253, 40
	v_readlane_b32 s39, v253, 41
	s_add_u32 s2, s38, s2
	s_addc_u32 s3, s39, s3
	s_add_u32 s2, s2, s36
	s_waitcnt lgkmcnt(0)
	v_add_f32_e32 v114, v114, v115
	s_addc_u32 s3, s3, s37
	global_store_dword v138, v114, s[2:3] offset:64
.LBB0_150:
	s_or_b64 exec, exec, s[0:1]
	v_pk_mul_f32 v[100:101], v[104:105], v[100:101]
	v_pk_mul_f32 v[98:99], v[102:103], v[98:99]
	v_mul_f32_e32 v102, 0xbfb8aa3b, v94
	v_mov_b32_e32 v104, v94
	v_mul_f32_e32 v94, 0xbfb8aa3b, v95
	v_exp_f32_e32 v94, v94
	v_exp_f32_e32 v102, v102
	v_mov_b32_e32 v103, v106
	v_mov_b32_e32 v105, v52
	v_add_f32_e32 v94, 1.0, v94
	v_add_f32_e32 v102, 1.0, v102
	v_rcp_f32_e32 v106, v94
	v_rcp_f32_e32 v102, v102
	v_mov_b32_e32 v94, v95
	v_mov_b32_e32 v95, v53
	v_pk_mul_f32 v[94:95], v[94:95], v[106:107]
	v_pk_mul_f32 v[102:103], v[104:105], v[102:103]
	v_mul_f32_e32 v94, v94, v95
	v_mul_f32_e32 v95, 0xbfb8aa3b, v96
	v_mov_b32_e32 v104, v96
	v_mul_f32_e32 v96, 0xbfb8aa3b, v97
	v_exp_f32_e32 v95, v95
	v_exp_f32_e32 v96, v96
	v_mul_f32_e32 v102, v102, v103
	v_cvt_pk_bf16_f32 v94, v102, v94
	v_add_f32_e32 v95, 1.0, v95
	v_add_f32_e32 v96, 1.0, v96
	v_rcp_f32_e32 v102, v95
	v_mov_b32_e32 v103, v108
	v_rcp_f32_e32 v108, v96
	v_mov_b32_e32 v105, v54
	v_mov_b32_e32 v96, v97
	v_mov_b32_e32 v97, v55
	v_pk_mul_f32 v[102:103], v[104:105], v[102:103]
	v_pk_mul_f32 v[96:97], v[96:97], v[108:109]
	v_mul_f32_e32 v95, v102, v103
	v_mul_f32_e32 v96, v96, v97
	v_cvt_pk_bf16_f32 v95, v95, v96
	v_add_u32_e32 v96, s16, v180
	v_ashrrev_i32_e32 v97, 31, v96
	v_lshlrev_b64 v[96:97], 12, v[96:97]
	v_lshl_add_u64 v[96:97], s[94:95], 0, v[96:97]
	v_mov_b32_e32 v131, v147
	v_lshl_add_u64 v[96:97], v[96:97], 0, v[130:131]
	global_store_dwordx2 v[96:97], v[94:95], off
	v_cndmask_b32_e64 v95, v98, v110, s[14:15]
	v_cndmask_b32_e64 v97, v99, v111, s[14:15]
	v_cndmask_b32_e64 v103, v100, v112, s[14:15]
	v_cndmask_b32_e64 v105, v101, v113, s[14:15]
	v_cndmask_b32_e64 v94, v98, v110, s[4:5]
	v_mov_b32_dpp v96, v95 row_ror:2 row_mask:0xf bank_mask:0xf bound_ctrl:1
	v_cndmask_b32_e64 v95, v99, v111, s[4:5]
	v_mov_b32_dpp v97, v97 row_ror:2 row_mask:0xf bank_mask:0xf bound_ctrl:1
	v_cndmask_b32_e64 v102, v100, v112, s[4:5]
	v_mov_b32_dpp v104, v103 row_ror:2 row_mask:0xf bank_mask:0xf bound_ctrl:1
	v_cndmask_b32_e64 v103, v101, v113, s[4:5]
	v_mov_b32_dpp v105, v105 row_ror:2 row_mask:0xf bank_mask:0xf bound_ctrl:1
	v_mov_b32_dpp v94, v94 row_ror:1 row_mask:0xf bank_mask:0xf bound_ctrl:1
	v_mov_b32_dpp v95, v95 row_ror:1 row_mask:0xf bank_mask:0xf bound_ctrl:1
	v_mov_b32_dpp v102, v102 row_ror:1 row_mask:0xf bank_mask:0xf bound_ctrl:1
	v_mov_b32_dpp v103, v103 row_ror:1 row_mask:0xf bank_mask:0xf bound_ctrl:1
	v_pk_mul_f32 v[104:105], v[84:85], v[104:105]
	v_pk_mul_f32 v[96:97], v[82:83], v[96:97]
	v_pk_fma_f32 v[102:103], v[78:79], v[102:103], v[104:105]
	v_pk_fma_f32 v[94:95], v[76:77], v[94:95], v[96:97]
	v_pk_fma_f32 v[96:97], v[100:101], v[74:75], v[102:103]
	v_pk_fma_f32 v[94:95], v[98:99], v[72:73], v[94:95]
	v_pk_mul_f32 v[92:93], v[92:93], v[96:97]
	v_pk_mul_f32 v[90:91], v[90:91], v[94:95]
	v_mul_f32_e32 v95, v93, v93
	v_mul_f32_e32 v94, v91, v91
	v_fmac_f32_e32 v94, v90, v90
	v_fmac_f32_e32 v95, v92, v92
	v_add_f32_e32 v94, v94, v95
	v_mov_b32_e32 v95, v94
	s_nop 1
	v_permlane16_swap_b32_e32 v95, v94
	s_waitcnt lgkmcnt(0)
	v_add_f32_e32 v94, v94, v95
	v_mov_b32_e32 v95, v94
	s_nop 1
	v_permlane32_swap_b32_e32 v95, v94
	s_and_saveexec_b64 s[0:1], s[6:7]
	s_cbranch_execz .LBB0_152
	s_ashr_i32 s75, s74, 31
	s_lshl_b64 s[2:3], s[74:75], 16
	s_lshl_b64 s[36:37], s[68:69], 10
	v_readlane_b32 s38, v253, 40
	v_readlane_b32 s39, v253, 41
	s_add_u32 s2, s38, s2
	s_addc_u32 s3, s39, s3
	s_add_u32 s2, s2, s36
	s_waitcnt lgkmcnt(0)
	v_add_f32_e32 v94, v94, v95
	s_addc_u32 s3, s3, s37
	global_store_dword v138, v94, s[2:3] offset:128
; __device__ __forceinline__ unsigned cvt_pk_bf16(float lo, float hi) { unsigned r; asm volatile("v_cvt_pk_bf16_f32 %0, %1, %2" : "=v"(r) : "v"(lo), "v"(hi)); return r; }
; __device__ __forceinline__ float silu_f(float g) { return g * __builtin_amdgcn_rcpf(1.0f + __builtin_amdgcn_exp2f(-1.4426950408889634f * g)); }
;     __device__ __forceinline__ void operator()(f32x4 (&acc)[2][2][4][2], const Unit& u, int wr, int wc, int fr, int fq, PG8_LAS unsigned char* lds) const {
;     ...
;                 if (g >= 1) prev = XB[((g - 1) * 4 + wc) * 8 + fq * 2 + (fr & 1)];
; #pragma unroll
;                 for (int m = 0; m < 4; ++m) {
;                     const f32x4 uc = acc[ai][0][m][1], cb = acc[ai][0][m][0], gt = acc[ai][1][m][1];
;                     f32x4 v1, v2;
; #pragma unroll
;                     for (int i = 0; i < 4; ++i) {
;                         const float s1 = (fr == 15) ? prev[i] : uc[i], s2 = (fr >= 14) ? prev[i] : uc[i];
;                         v1[i] = __int_as_float(__builtin_amdgcn_mov_dpp(__float_as_int(s1), 0x121, 0xf, 0xf, true));
;                         v2[i] = __int_as_float(__builtin_amdgcn_mov_dpp(__float_as_int(s2), 0x122, 0xf, 0xf, true));
;                     }
;                     const f32x4 raw = cb * (w0 * v2 + w1 * v1 + w2 * uc);
;                     float ss = (raw[0] * raw[0] + raw[1] * raw[1]) + (raw[2] * raw[2] + raw[3] * raw[3]);
;                     ss += __shfl_xor(ss, 16); ss += __shfl_xor(ss, 32);
;                     const int rl = ai * HALF + wr * 64 + m * 16 + fr;
;                     const bool def = deferred_tile && (rl < 2);
;                     if (fq == 0) SSCT[((size_t)u.pm * 64 + j * 4 + wc) * 256 + rl] = def ? 0.f : ss;
;                     u32x2 z;
;                     z.x = cvt_pk_bf16(raw[0] * gn[0] * silu_f(gt[0]), raw[1] * gn[1] * silu_f(gt[1]));
;                     z.y = cvt_pk_bf16(raw[2] * gn[2] * silu_f(gt[2]), raw[3] * gn[3] * silu_f(gt[3]));
;                     *(u32x2*)(MIX + (size_t)(u.pm * BM + rl) * 2048 + col) = z;
.LBB0_152:
	s_or_b64 exec, exec, s[0:1]
	v_mul_f32_e32 v94, 0xbfb8aa3b, v86
	v_mov_b32_e32 v96, v86
	v_mul_f32_e32 v86, 0xbfb8aa3b, v87
	v_exp_f32_e32 v94, v94
	v_exp_f32_e32 v86, v86
	s_waitcnt lgkmcnt(0)
	v_mov_b32_e32 v95, v90
	v_mov_b32_e32 v97, v52
	v_add_f32_e32 v94, 1.0, v94
	v_add_f32_e32 v86, 1.0, v86
	v_rcp_f32_e32 v94, v94
	v_rcp_f32_e32 v90, v86
	v_mov_b32_e32 v86, v87
	v_mov_b32_e32 v87, v53
	v_pk_mul_f32 v[94:95], v[96:97], v[94:95]
	v_pk_mul_f32 v[86:87], v[86:87], v[90:91]
	v_mul_f32_e32 v94, v94, v95
	v_mul_f32_e32 v86, v86, v87
	v_cvt_pk_bf16_f32 v86, v94, v86
	v_mul_f32_e32 v87, 0xbfb8aa3b, v88
	v_mov_b32_e32 v94, v88
	v_mul_f32_e32 v88, 0xbfb8aa3b, v89
	v_exp_f32_e32 v87, v87
	v_exp_f32_e32 v88, v88
	v_mov_b32_e32 v91, v92
	v_mov_b32_e32 v95, v54
	v_add_f32_e32 v87, 1.0, v87
	v_add_f32_e32 v88, 1.0, v88
	v_rcp_f32_e32 v90, v87
	v_rcp_f32_e32 v92, v88
	v_mov_b32_e32 v88, v89
	v_mov_b32_e32 v89, v55
	v_pk_mul_f32 v[90:91], v[94:95], v[90:91]
	v_pk_mul_f32 v[88:89], v[88:89], v[92:93]
	v_mul_f32_e32 v87, v90, v91
	v_mul_f32_e32 v88, v88, v89
	v_cvt_pk_bf16_f32 v87, v87, v88
	v_add_u32_e32 v88, s16, v181
	v_ashrrev_i32_e32 v89, 31, v88
	v_lshlrev_b64 v[88:89], 12, v[88:89]
	v_lshl_add_u64 v[88:89], s[94:95], 0, v[88:89]
	v_lshl_add_u64 v[88:89], v[88:89], 0, v[130:131]
	global_store_dwordx2 v[88:89], v[86:87], off
	v_cndmask_b32_e64 v87, v134, v98, s[14:15]
	v_cndmask_b32_e64 v89, v135, v99, s[14:15]
	v_cndmask_b32_e64 v91, v136, v100, s[14:15]
	v_cndmask_b32_e64 v93, v137, v101, s[14:15]
	v_cndmask_b32_e64 v86, v134, v98, s[4:5]
	v_mov_b32_dpp v88, v87 row_ror:2 row_mask:0xf bank_mask:0xf bound_ctrl:1
	v_cndmask_b32_e64 v87, v135, v99, s[4:5]
	v_mov_b32_dpp v89, v89 row_ror:2 row_mask:0xf bank_mask:0xf bound_ctrl:1
	v_cndmask_b32_e64 v90, v136, v100, s[4:5]
	v_mov_b32_dpp v92, v91 row_ror:2 row_mask:0xf bank_mask:0xf bound_ctrl:1
	v_cndmask_b32_e64 v91, v137, v101, s[4:5]
	v_mov_b32_dpp v93, v93 row_ror:2 row_mask:0xf bank_mask:0xf bound_ctrl:1
	v_mov_b32_dpp v86, v86 row_ror:1 row_mask:0xf bank_mask:0xf bound_ctrl:1
	v_mov_b32_dpp v87, v87 row_ror:1 row_mask:0xf bank_mask:0xf bound_ctrl:1
	v_mov_b32_dpp v90, v90 row_ror:1 row_mask:0xf bank_mask:0xf bound_ctrl:1
	v_mov_b32_dpp v91, v91 row_ror:1 row_mask:0xf bank_mask:0xf bound_ctrl:1
	v_pk_mul_f32 v[88:89], v[82:83], v[88:89]
	v_pk_mul_f32 v[92:93], v[84:85], v[92:93]
	v_pk_fma_f32 v[86:87], v[76:77], v[86:87], v[88:89]
	v_pk_fma_f32 v[90:91], v[78:79], v[90:91], v[92:93]
	v_pk_fma_f32 v[86:87], v[134:135], v[72:73], v[86:87]
	v_pk_fma_f32 v[88:89], v[136:137], v[74:75], v[90:91]
	v_pk_mul_f32 v[68:69], v[68:69], v[86:87]
	v_pk_mul_f32 v[70:71], v[70:71], v[88:89]
	v_mul_f32_e32 v86, v69, v69
	v_mul_f32_e32 v87, v71, v71
	v_fmac_f32_e32 v86, v68, v68
	v_fmac_f32_e32 v87, v70, v70
	v_add_f32_e32 v86, v86, v87
	v_mov_b32_e32 v87, v86
	s_nop 1
	v_permlane16_swap_b32_e32 v87, v86
	s_waitcnt lgkmcnt(0)
	v_add_f32_e32 v86, v86, v87
	v_mov_b32_e32 v87, v86
	s_nop 1
	v_permlane32_swap_b32_e32 v87, v86
	s_and_saveexec_b64 s[0:1], s[6:7]
	s_cbranch_execz .LBB0_154
	s_ashr_i32 s75, s74, 31
	s_lshl_b64 s[2:3], s[74:75], 16
	s_lshl_b64 s[36:37], s[68:69], 10
	v_readlane_b32 s38, v253, 40
	v_readlane_b32 s39, v253, 41
	s_add_u32 s2, s38, s2
	s_addc_u32 s3, s39, s3
	s_add_u32 s2, s2, s36
	s_waitcnt lgkmcnt(0)
	v_add_f32_e32 v86, v86, v87
	s_addc_u32 s3, s3, s37
	global_store_dword v138, v86, s[2:3] offset:192
.LBB0_154:
	s_or_b64 exec, exec, s[0:1]
	v_pk_mul_f32 v[58:59], v[62:63], v[58:59]
	v_pk_mul_f32 v[56:57], v[60:61], v[56:57]
	v_mul_f32_e32 v60, 0xbfb8aa3b, v48
	v_mov_b32_e32 v62, v48
	v_mul_f32_e32 v48, 0xbfb8aa3b, v49
	v_exp_f32_e32 v48, v48
	v_exp_f32_e32 v60, v60
	v_mov_b32_e32 v61, v68
	v_mov_b32_e32 v63, v52
	v_add_f32_e32 v48, 1.0, v48
	v_add_f32_e32 v60, 1.0, v60
	v_rcp_f32_e32 v68, v48
	v_rcp_f32_e32 v60, v60
	v_mov_b32_e32 v48, v49
	v_mov_b32_e32 v49, v53
	v_pk_mul_f32 v[48:49], v[48:49], v[68:69]
	v_pk_mul_f32 v[60:61], v[62:63], v[60:61]
	v_mul_f32_e32 v48, v48, v49
	v_mul_f32_e32 v49, 0xbfb8aa3b, v50
	v_mov_b32_e32 v62, v50
	v_mul_f32_e32 v50, 0xbfb8aa3b, v51
	v_exp_f32_e32 v49, v49
	v_exp_f32_e32 v50, v50
	v_mul_f32_e32 v60, v60, v61
	v_cvt_pk_bf16_f32 v48, v60, v48
	v_add_f32_e32 v49, 1.0, v49
	v_add_f32_e32 v50, 1.0, v50
	v_rcp_f32_e32 v60, v49
	v_mov_b32_e32 v61, v70
	v_rcp_f32_e32 v70, v50
	v_mov_b32_e32 v63, v54
	v_mov_b32_e32 v50, v51
	v_mov_b32_e32 v51, v55
	v_pk_mul_f32 v[60:61], v[62:63], v[60:61]
	v_pk_mul_f32 v[50:51], v[50:51], v[70:71]
	v_mul_f32_e32 v49, v60, v61
	v_mul_f32_e32 v50, v50, v51
	v_cvt_pk_bf16_f32 v49, v49, v50
	v_add_u32_e32 v50, s16, v182
	v_ashrrev_i32_e32 v51, 31, v50
	v_lshlrev_b64 v[50:51], 12, v[50:51]
	v_lshl_add_u64 v[50:51], s[94:95], 0, v[50:51]
	v_mov_b32_e32 v131, v147
	v_lshl_add_u64 v[50:51], v[50:51], 0, v[130:131]
	global_store_dwordx2 v[50:51], v[48:49], off
	ds_read_b128 v[48:51], v178 offset:512
	s_waitcnt lgkmcnt(0)
	v_cndmask_b32_e64 v60, v56, v48, s[4:5]
	v_cndmask_b32_e64 v61, v56, v48, s[14:15]
	s_nop 0
	v_mov_b32_dpp v48, v60 row_ror:1 row_mask:0xf bank_mask:0xf bound_ctrl:1
	v_cndmask_b32_e64 v62, v57, v49, s[14:15]
	v_mov_b32_dpp v60, v61 row_ror:2 row_mask:0xf bank_mask:0xf bound_ctrl:1
	v_cndmask_b32_e64 v61, v57, v49, s[4:5]
	v_cndmask_b32_e64 v63, v58, v50, s[14:15]
	v_cndmask_b32_e64 v68, v59, v51, s[14:15]
	v_mov_b32_dpp v49, v61 row_ror:1 row_mask:0xf bank_mask:0xf bound_ctrl:1
	v_mov_b32_dpp v61, v62 row_ror:2 row_mask:0xf bank_mask:0xf bound_ctrl:1
	v_cndmask_b32_e64 v62, v58, v50, s[4:5]
	v_pk_mul_f32 v[60:61], v[82:83], v[60:61]
	s_nop 0
	v_mov_b32_dpp v50, v62 row_ror:1 row_mask:0xf bank_mask:0xf bound_ctrl:1
	v_mov_b32_dpp v62, v63 row_ror:2 row_mask:0xf bank_mask:0xf bound_ctrl:1
	v_cndmask_b32_e64 v63, v59, v51, s[4:5]
	v_pk_fma_f32 v[48:49], v[76:77], v[48:49], v[60:61]
	s_nop 0
	v_mov_b32_dpp v51, v63 row_ror:1 row_mask:0xf bank_mask:0xf bound_ctrl:1
	v_mov_b32_dpp v63, v68 row_ror:2 row_mask:0xf bank_mask:0xf bound_ctrl:1
	v_pk_mul_f32 v[62:63], v[84:85], v[62:63]
	v_pk_fma_f32 v[48:49], v[56:57], v[72:73], v[48:49]
	v_pk_fma_f32 v[50:51], v[78:79], v[50:51], v[62:63]
	v_pk_mul_f32 v[44:45], v[44:45], v[48:49]
	v_pk_fma_f32 v[50:51], v[58:59], v[74:75], v[50:51]
	v_mul_f32_e32 v48, v45, v45
	v_pk_mul_f32 v[46:47], v[46:47], v[50:51]
	v_fmac_f32_e32 v48, v44, v44
	v_mul_f32_e32 v49, v47, v47
	v_fmac_f32_e32 v49, v46, v46
	v_add_f32_e32 v48, v48, v49
	v_mov_b32_e32 v49, v48
	s_nop 1
	v_permlane16_swap_b32_e32 v49, v48
	s_waitcnt lgkmcnt(0)
	v_add_f32_e32 v48, v48, v49
	v_mov_b32_e32 v49, v48
	s_nop 1
	v_permlane32_swap_b32_e32 v49, v48
	s_and_saveexec_b64 s[0:1], s[6:7]
	s_cbranch_execz .LBB0_156
	s_ashr_i32 s75, s74, 31
	s_lshl_b64 s[2:3], s[74:75], 16
	s_lshl_b64 s[16:17], s[68:69], 10
	v_readlane_b32 s36, v253, 40
	v_readlane_b32 s37, v253, 41
	s_add_u32 s2, s36, s2
	s_addc_u32 s3, s37, s3
	s_add_u32 s2, s2, s16
	s_waitcnt lgkmcnt(0)
	v_add_f32_e32 v48, v48, v49
	s_addc_u32 s3, s3, s17
	global_store_dword v138, v48, s[2:3] offset:512
; __device__ __forceinline__ unsigned cvt_pk_bf16(float lo, float hi) { unsigned r; asm volatile("v_cvt_pk_bf16_f32 %0, %1, %2" : "=v"(r) : "v"(lo), "v"(hi)); return r; }
; __device__ __forceinline__ float silu_f(float g) { return g * __builtin_amdgcn_rcpf(1.0f + __builtin_amdgcn_exp2f(-1.4426950408889634f * g)); }
;     __device__ __forceinline__ void operator()(f32x4 (&acc)[2][2][4][2], const Unit& u, int wr, int wc, int fr, int fq, PG8_LAS unsigned char* lds) const {
;     ...
;                 for (int m = 0; m < 4; ++m) {
;                     const f32x4 uc = acc[ai][0][m][1], cb = acc[ai][0][m][0], gt = acc[ai][1][m][1];
;                     f32x4 v1, v2;
; #pragma unroll
;                     for (int i = 0; i < 4; ++i) {
;                         const float s1 = (fr == 15) ? prev[i] : uc[i], s2 = (fr >= 14) ? prev[i] : uc[i];
;                         v1[i] = __int_as_float(__builtin_amdgcn_mov_dpp(__float_as_int(s1), 0x121, 0xf, 0xf, true));
;                         v2[i] = __int_as_float(__builtin_amdgcn_mov_dpp(__float_as_int(s2), 0x122, 0xf, 0xf, true));
;                     }
;                     const f32x4 raw = cb * (w0 * v2 + w1 * v1 + w2 * uc);
;                     float ss = (raw[0] * raw[0] + raw[1] * raw[1]) + (raw[2] * raw[2] + raw[3] * raw[3]);
;                     ss += __shfl_xor(ss, 16); ss += __shfl_xor(ss, 32);
;                     const int rl = ai * HALF + wr * 64 + m * 16 + fr;
;                     const bool def = deferred_tile && (rl < 2);
;                     if (fq == 0) SSCT[((size_t)u.pm * 64 + j * 4 + wc) * 256 + rl] = def ? 0.f : ss;
;                     u32x2 z;
;                     z.x = cvt_pk_bf16(raw[0] * gn[0] * silu_f(gt[0]), raw[1] * gn[1] * silu_f(gt[1]));
;                     z.y = cvt_pk_bf16(raw[2] * gn[2] * silu_f(gt[2]), raw[3] * gn[3] * silu_f(gt[3]));
;                     *(u32x2*)(MIX + (size_t)(u.pm * BM + rl) * 2048 + col) = z;
.LBB0_156:
	s_or_b64 exec, exec, s[0:1]
	v_pk_mul_f32 v[38:39], v[42:43], v[38:39]
	v_pk_mul_f32 v[36:37], v[40:41], v[36:37]
	v_mul_f32_e32 v40, 0xbfb8aa3b, v32
	v_mov_b32_e32 v42, v32
	v_mul_f32_e32 v32, 0xbfb8aa3b, v33
	v_exp_f32_e32 v32, v32
	v_exp_f32_e32 v40, v40
	v_mov_b32_e32 v41, v44
	v_mov_b32_e32 v43, v52
	v_add_f32_e32 v32, 1.0, v32
	v_add_f32_e32 v40, 1.0, v40
	v_rcp_f32_e32 v44, v32
	v_rcp_f32_e32 v40, v40
	v_mov_b32_e32 v32, v33
	v_mov_b32_e32 v33, v53
	v_pk_mul_f32 v[32:33], v[32:33], v[44:45]
	v_pk_mul_f32 v[40:41], v[42:43], v[40:41]
	v_mul_f32_e32 v32, v32, v33
	v_mul_f32_e32 v33, 0xbfb8aa3b, v34
	v_mov_b32_e32 v42, v34
	v_mul_f32_e32 v34, 0xbfb8aa3b, v35
	v_exp_f32_e32 v33, v33
	v_exp_f32_e32 v34, v34
	v_mul_f32_e32 v40, v40, v41
	v_cvt_pk_bf16_f32 v32, v40, v32
	v_add_f32_e32 v33, 1.0, v33
	v_add_f32_e32 v34, 1.0, v34
	v_rcp_f32_e32 v40, v33
	v_mov_b32_e32 v41, v46
	v_rcp_f32_e32 v46, v34
	v_mov_b32_e32 v43, v54
	v_mov_b32_e32 v34, v35
	v_mov_b32_e32 v35, v55
	v_pk_mul_f32 v[40:41], v[42:43], v[40:41]
	v_pk_mul_f32 v[34:35], v[34:35], v[46:47]
	v_mul_f32_e32 v33, v40, v41
	v_mul_f32_e32 v34, v34, v35
	v_cvt_pk_bf16_f32 v33, v33, v34
	v_add_u32_e32 v34, 0x80, v132
	v_ashrrev_i32_e32 v35, 31, v34
	v_lshlrev_b64 v[34:35], 12, v[34:35]
	v_lshl_add_u64 v[34:35], s[94:95], 0, v[34:35]
	v_lshl_add_u64 v[34:35], v[34:35], 0, v[130:131]
	global_store_dwordx2 v[34:35], v[32:33], off
	v_cndmask_b32_e64 v33, v36, v56, s[14:15]
	v_cndmask_b32_e64 v35, v37, v57, s[14:15]
	v_cndmask_b32_e64 v41, v38, v58, s[14:15]
	v_cndmask_b32_e64 v43, v39, v59, s[14:15]
	v_cndmask_b32_e64 v32, v36, v56, s[4:5]
	v_mov_b32_dpp v34, v33 row_ror:2 row_mask:0xf bank_mask:0xf bound_ctrl:1
	v_cndmask_b32_e64 v33, v37, v57, s[4:5]
	v_mov_b32_dpp v35, v35 row_ror:2 row_mask:0xf bank_mask:0xf bound_ctrl:1
	v_cndmask_b32_e64 v40, v38, v58, s[4:5]
	v_mov_b32_dpp v42, v41 row_ror:2 row_mask:0xf bank_mask:0xf bound_ctrl:1
	v_cndmask_b32_e64 v41, v39, v59, s[4:5]
	v_mov_b32_dpp v43, v43 row_ror:2 row_mask:0xf bank_mask:0xf bound_ctrl:1
	v_mov_b32_dpp v32, v32 row_ror:1 row_mask:0xf bank_mask:0xf bound_ctrl:1
	v_mov_b32_dpp v33, v33 row_ror:1 row_mask:0xf bank_mask:0xf bound_ctrl:1
	v_mov_b32_dpp v40, v40 row_ror:1 row_mask:0xf bank_mask:0xf bound_ctrl:1
	v_mov_b32_dpp v41, v41 row_ror:1 row_mask:0xf bank_mask:0xf bound_ctrl:1
	v_pk_mul_f32 v[42:43], v[84:85], v[42:43]
	v_pk_mul_f32 v[34:35], v[82:83], v[34:35]
	v_pk_fma_f32 v[40:41], v[78:79], v[40:41], v[42:43]
	v_pk_fma_f32 v[32:33], v[76:77], v[32:33], v[34:35]
	v_pk_fma_f32 v[34:35], v[38:39], v[74:75], v[40:41]
	v_pk_fma_f32 v[32:33], v[36:37], v[72:73], v[32:33]
	v_pk_mul_f32 v[30:31], v[30:31], v[34:35]
	v_pk_mul_f32 v[28:29], v[28:29], v[32:33]
	v_mul_f32_e32 v33, v31, v31
	v_mul_f32_e32 v32, v29, v29
	v_fmac_f32_e32 v32, v28, v28
	v_fmac_f32_e32 v33, v30, v30
	v_add_f32_e32 v32, v32, v33
	v_mov_b32_e32 v33, v32
	s_nop 1
	v_permlane16_swap_b32_e32 v33, v32
	s_waitcnt lgkmcnt(0)
	v_add_f32_e32 v32, v32, v33
	v_mov_b32_e32 v33, v32
	s_nop 1
	v_permlane32_swap_b32_e32 v33, v32
	s_and_saveexec_b64 s[0:1], s[6:7]
	s_cbranch_execz .LBB0_158
	s_ashr_i32 s75, s74, 31
	s_lshl_b64 s[2:3], s[74:75], 16
	s_lshl_b64 s[16:17], s[68:69], 10
	v_readlane_b32 s36, v253, 40
	v_readlane_b32 s37, v253, 41
	s_add_u32 s2, s36, s2
	s_addc_u32 s3, s37, s3
	s_add_u32 s2, s2, s16
	s_waitcnt lgkmcnt(0)
	v_add_f32_e32 v32, v32, v33
	s_addc_u32 s3, s3, s17
	global_store_dword v138, v32, s[2:3] offset:576
; __device__ __forceinline__ unsigned cvt_pk_bf16(float lo, float hi) { unsigned r; asm volatile("v_cvt_pk_bf16_f32 %0, %1, %2" : "=v"(r) : "v"(lo), "v"(hi)); return r; }
; __device__ __forceinline__ float silu_f(float g) { return g * __builtin_amdgcn_rcpf(1.0f + __builtin_amdgcn_exp2f(-1.4426950408889634f * g)); }
;     __device__ __forceinline__ void operator()(f32x4 (&acc)[2][2][4][2], const Unit& u, int wr, int wc, int fr, int fq, PG8_LAS unsigned char* lds) const {
;     ...
;                 for (int m = 0; m < 4; ++m) {
;                     const f32x4 uc = acc[ai][0][m][1], cb = acc[ai][0][m][0], gt = acc[ai][1][m][1];
;                     f32x4 v1, v2;
; #pragma unroll
;                     for (int i = 0; i < 4; ++i) {
;                         const float s1 = (fr == 15) ? prev[i] : uc[i], s2 = (fr >= 14) ? prev[i] : uc[i];
;                         v1[i] = __int_as_float(__builtin_amdgcn_mov_dpp(__float_as_int(s1), 0x121, 0xf, 0xf, true));
;                         v2[i] = __int_as_float(__builtin_amdgcn_mov_dpp(__float_as_int(s2), 0x122, 0xf, 0xf, true));
;                     }
;                     const f32x4 raw = cb * (w0 * v2 + w1 * v1 + w2 * uc);
;                     float ss = (raw[0] * raw[0] + raw[1] * raw[1]) + (raw[2] * raw[2] + raw[3] * raw[3]);
;                     ss += __shfl_xor(ss, 16); ss += __shfl_xor(ss, 32);
;                     const int rl = ai * HALF + wr * 64 + m * 16 + fr;
;                     const bool def = deferred_tile && (rl < 2);
;                     if (fq == 0) SSCT[((size_t)u.pm * 64 + j * 4 + wc) * 256 + rl] = def ? 0.f : ss;
;                     u32x2 z;
;                     z.x = cvt_pk_bf16(raw[0] * gn[0] * silu_f(gt[0]), raw[1] * gn[1] * silu_f(gt[1]));
;                     z.y = cvt_pk_bf16(raw[2] * gn[2] * silu_f(gt[2]), raw[3] * gn[3] * silu_f(gt[3]));
;                     *(u32x2*)(MIX + (size_t)(u.pm * BM + rl) * 2048 + col) = z;
.LBB0_158:
	s_or_b64 exec, exec, s[0:1]
	v_pk_mul_f32 v[22:23], v[26:27], v[22:23]
	v_pk_mul_f32 v[20:21], v[24:25], v[20:21]
	v_mul_f32_e32 v24, 0xbfb8aa3b, v16
	v_mov_b32_e32 v26, v16
	v_mul_f32_e32 v16, 0xbfb8aa3b, v17
	v_exp_f32_e32 v16, v16
	v_exp_f32_e32 v24, v24
	v_mov_b32_e32 v25, v28
	v_mov_b32_e32 v27, v52
	v_add_f32_e32 v16, 1.0, v16
	v_add_f32_e32 v24, 1.0, v24
	v_rcp_f32_e32 v28, v16
	v_rcp_f32_e32 v24, v24
	v_mov_b32_e32 v16, v17
	v_mov_b32_e32 v17, v53
	v_pk_mul_f32 v[16:17], v[16:17], v[28:29]
	v_pk_mul_f32 v[24:25], v[26:27], v[24:25]
	v_mul_f32_e32 v16, v16, v17
	v_mul_f32_e32 v17, 0xbfb8aa3b, v18
	v_mov_b32_e32 v26, v18
	v_mul_f32_e32 v18, 0xbfb8aa3b, v19
	v_exp_f32_e32 v17, v17
	v_exp_f32_e32 v18, v18
	v_mul_f32_e32 v24, v24, v25
	v_cvt_pk_bf16_f32 v16, v24, v16
	v_add_f32_e32 v17, 1.0, v17
	v_add_f32_e32 v18, 1.0, v18
	v_rcp_f32_e32 v24, v17
	v_mov_b32_e32 v25, v30
	v_rcp_f32_e32 v30, v18
	v_mov_b32_e32 v27, v54
	v_mov_b32_e32 v18, v19
	v_mov_b32_e32 v19, v55
	v_pk_mul_f32 v[24:25], v[26:27], v[24:25]
	v_pk_mul_f32 v[18:19], v[18:19], v[30:31]
	v_mul_f32_e32 v17, v24, v25
	v_mul_f32_e32 v18, v18, v19
	v_cvt_pk_bf16_f32 v17, v17, v18
	v_add_u32_e32 v18, 0x90, v132
	v_ashrrev_i32_e32 v19, 31, v18
	v_lshlrev_b64 v[18:19], 12, v[18:19]
	v_lshl_add_u64 v[18:19], s[94:95], 0, v[18:19]
	v_mov_b32_e32 v131, v147
	v_lshl_add_u64 v[18:19], v[18:19], 0, v[130:131]
	global_store_dwordx2 v[18:19], v[16:17], off
	v_cndmask_b32_e64 v17, v20, v36, s[14:15]
	v_cndmask_b32_e64 v19, v21, v37, s[14:15]
	v_cndmask_b32_e64 v25, v22, v38, s[14:15]
	v_cndmask_b32_e64 v27, v23, v39, s[14:15]
	v_cndmask_b32_e64 v16, v20, v36, s[4:5]
	v_mov_b32_dpp v18, v17 row_ror:2 row_mask:0xf bank_mask:0xf bound_ctrl:1
	v_cndmask_b32_e64 v17, v21, v37, s[4:5]
	v_mov_b32_dpp v19, v19 row_ror:2 row_mask:0xf bank_mask:0xf bound_ctrl:1
	v_cndmask_b32_e64 v24, v22, v38, s[4:5]
	v_mov_b32_dpp v26, v25 row_ror:2 row_mask:0xf bank_mask:0xf bound_ctrl:1
	v_cndmask_b32_e64 v25, v23, v39, s[4:5]
	v_mov_b32_dpp v27, v27 row_ror:2 row_mask:0xf bank_mask:0xf bound_ctrl:1
	v_mov_b32_dpp v16, v16 row_ror:1 row_mask:0xf bank_mask:0xf bound_ctrl:1
	v_mov_b32_dpp v17, v17 row_ror:1 row_mask:0xf bank_mask:0xf bound_ctrl:1
	v_mov_b32_dpp v24, v24 row_ror:1 row_mask:0xf bank_mask:0xf bound_ctrl:1
	v_mov_b32_dpp v25, v25 row_ror:1 row_mask:0xf bank_mask:0xf bound_ctrl:1
	v_pk_mul_f32 v[26:27], v[84:85], v[26:27]
	v_pk_mul_f32 v[18:19], v[82:83], v[18:19]
	v_pk_fma_f32 v[24:25], v[78:79], v[24:25], v[26:27]
	v_pk_fma_f32 v[16:17], v[76:77], v[16:17], v[18:19]
	v_pk_fma_f32 v[18:19], v[22:23], v[74:75], v[24:25]
	v_pk_fma_f32 v[16:17], v[20:21], v[72:73], v[16:17]
	v_pk_mul_f32 v[14:15], v[14:15], v[18:19]
	v_pk_mul_f32 v[12:13], v[12:13], v[16:17]
	v_mul_f32_e32 v17, v15, v15
	v_mul_f32_e32 v16, v13, v13
	v_fmac_f32_e32 v16, v12, v12
	v_fmac_f32_e32 v17, v14, v14
	v_add_f32_e32 v16, v16, v17
	v_mov_b32_e32 v17, v16
	s_nop 1
	v_permlane16_swap_b32_e32 v17, v16
	s_waitcnt lgkmcnt(0)
	v_add_f32_e32 v16, v16, v17
	v_mov_b32_e32 v17, v16
	s_nop 1
	v_permlane32_swap_b32_e32 v17, v16
	s_and_saveexec_b64 s[0:1], s[6:7]
	s_cbranch_execz .LBB0_160
	s_ashr_i32 s75, s74, 31
	s_lshl_b64 s[2:3], s[74:75], 16
	s_lshl_b64 s[16:17], s[68:69], 10
	v_readlane_b32 s36, v253, 40
	v_readlane_b32 s37, v253, 41
	s_add_u32 s2, s36, s2
	s_addc_u32 s3, s37, s3
	s_add_u32 s2, s2, s16
	s_waitcnt lgkmcnt(0)
	v_add_f32_e32 v16, v16, v17
	s_addc_u32 s3, s3, s17
	global_store_dword v138, v16, s[2:3] offset:640
.LBB0_160:
	s_or_b64 exec, exec, s[0:1]
	v_mul_f32_e32 v16, 0xbfb8aa3b, v8
	v_mov_b32_e32 v18, v8
	v_mul_f32_e32 v8, 0xbfb8aa3b, v9
	v_exp_f32_e32 v16, v16
	v_exp_f32_e32 v8, v8
	s_waitcnt lgkmcnt(0)
	v_mov_b32_e32 v17, v12
	v_mov_b32_e32 v19, v52
	v_add_f32_e32 v16, 1.0, v16
	v_add_f32_e32 v8, 1.0, v8
	v_rcp_f32_e32 v16, v16
	v_rcp_f32_e32 v12, v8
	v_mov_b32_e32 v8, v9
	v_mov_b32_e32 v9, v53
	v_pk_mul_f32 v[16:17], v[18:19], v[16:17]
	v_pk_mul_f32 v[8:9], v[8:9], v[12:13]
	v_mul_f32_e32 v16, v16, v17
	v_mul_f32_e32 v8, v8, v9
	v_cvt_pk_bf16_f32 v8, v16, v8
	v_mul_f32_e32 v9, 0xbfb8aa3b, v10
	v_mov_b32_e32 v16, v10
	v_mul_f32_e32 v10, 0xbfb8aa3b, v11
	v_exp_f32_e32 v9, v9
	v_exp_f32_e32 v10, v10
	v_mov_b32_e32 v13, v14
	v_mov_b32_e32 v17, v54
	v_add_f32_e32 v9, 1.0, v9
	v_add_f32_e32 v10, 1.0, v10
	v_rcp_f32_e32 v12, v9
	v_rcp_f32_e32 v14, v10
	v_mov_b32_e32 v10, v11
	v_mov_b32_e32 v11, v55
	v_pk_mul_f32 v[12:13], v[16:17], v[12:13]
	v_pk_mul_f32 v[10:11], v[10:11], v[14:15]
	v_mul_f32_e32 v9, v12, v13
	v_mul_f32_e32 v10, v10, v11
	v_cvt_pk_bf16_f32 v9, v9, v10
	v_add_u32_e32 v10, 0xa0, v132
	v_ashrrev_i32_e32 v11, 31, v10
	v_lshlrev_b64 v[10:11], 12, v[10:11]
	v_lshl_add_u64 v[10:11], s[94:95], 0, v[10:11]
	v_lshl_add_u64 v[10:11], v[10:11], 0, v[130:131]
	global_store_dwordx2 v[10:11], v[8:9], off
	v_cndmask_b32_e64 v9, v64, v20, s[14:15]
	v_cndmask_b32_e64 v11, v65, v21, s[14:15]
	v_cndmask_b32_e64 v13, v66, v22, s[14:15]
	v_cndmask_b32_e64 v15, v67, v23, s[14:15]
	v_cndmask_b32_e64 v8, v64, v20, s[4:5]
	v_mov_b32_dpp v10, v9 row_ror:2 row_mask:0xf bank_mask:0xf bound_ctrl:1
	v_cndmask_b32_e64 v9, v65, v21, s[4:5]
	v_mov_b32_dpp v11, v11 row_ror:2 row_mask:0xf bank_mask:0xf bound_ctrl:1
	v_cndmask_b32_e64 v12, v66, v22, s[4:5]
	v_mov_b32_dpp v14, v13 row_ror:2 row_mask:0xf bank_mask:0xf bound_ctrl:1
	v_cndmask_b32_e64 v13, v67, v23, s[4:5]
	v_mov_b32_dpp v15, v15 row_ror:2 row_mask:0xf bank_mask:0xf bound_ctrl:1
	v_mov_b32_dpp v8, v8 row_ror:1 row_mask:0xf bank_mask:0xf bound_ctrl:1
	v_mov_b32_dpp v9, v9 row_ror:1 row_mask:0xf bank_mask:0xf bound_ctrl:1
	v_mov_b32_dpp v12, v12 row_ror:1 row_mask:0xf bank_mask:0xf bound_ctrl:1
	v_mov_b32_dpp v13, v13 row_ror:1 row_mask:0xf bank_mask:0xf bound_ctrl:1
	v_pk_mul_f32 v[10:11], v[82:83], v[10:11]
	v_pk_mul_f32 v[14:15], v[84:85], v[14:15]
	v_pk_fma_f32 v[8:9], v[76:77], v[8:9], v[10:11]
	v_pk_fma_f32 v[12:13], v[78:79], v[12:13], v[14:15]
	v_pk_fma_f32 v[8:9], v[64:65], v[72:73], v[8:9]
	v_pk_fma_f32 v[10:11], v[66:67], v[74:75], v[12:13]
	v_pk_mul_f32 v[4:5], v[4:5], v[8:9]
	v_pk_mul_f32 v[6:7], v[6:7], v[10:11]
	v_mul_f32_e32 v8, v5, v5
	v_mul_f32_e32 v9, v7, v7
	v_fmac_f32_e32 v8, v4, v4
	v_fmac_f32_e32 v9, v6, v6
	v_add_f32_e32 v8, v8, v9
	v_mov_b32_e32 v9, v8
	s_nop 1
	v_permlane16_swap_b32_e32 v9, v8
	s_waitcnt lgkmcnt(0)
	v_add_f32_e32 v8, v8, v9
	v_mov_b32_e32 v9, v8
	s_nop 1
	v_permlane32_swap_b32_e32 v9, v8
	s_and_saveexec_b64 s[0:1], s[6:7]
	s_cbranch_execz .LBB0_162
	s_ashr_i32 s75, s74, 31
	s_lshl_b64 s[2:3], s[74:75], 16
	s_lshl_b64 s[16:17], s[68:69], 10
	v_readlane_b32 s36, v253, 40
	v_readlane_b32 s37, v253, 41
	s_add_u32 s2, s36, s2
	s_addc_u32 s3, s37, s3
	s_add_u32 s2, s2, s16
	s_waitcnt lgkmcnt(0)
	v_add_f32_e32 v8, v8, v9
	s_addc_u32 s3, s3, s17
	global_store_dword v138, v8, s[2:3] offset:704
